# GEMM->norm barriers P3|P4 and P9|P10 XCD-local as well (norm phases P4/P10 take their own XCD's row range when the run-time mapping flag is set)
# speedup vs baseline: 1.0156x; 1.0071x over previous
; __device__ __forceinline__ int lane_now() { int l; asm volatile("v_mbcnt_lo_u32_b32 %0, -1, 0\n\tv_mbcnt_hi_u32_b32 %0, -1, %0" : "=v"(l)); return l; }
; #define PG8_WAIT_V(n) asm volatile("s_waitcnt vmcnt(" #n ")" ::: "memory")
; #define lane (lane_now())
; template <class Epi, class Sched, bool ALIGN_EPI = false, bool SP2 = false>
; __device__ __forceinline__ void gemm_phase(PG8_LAS unsigned char* lds, const Gemm g, const Sched& S, const Epi& E, const int wid) {
;     const int lane = lane_now(), tid = wid * 64 + lane, wr = wid >> 2, wc = wid & 3, fr = lane & 15, fq = lane >> 4;
;     const int K = g.K, nt = K / BK;
;     unsigned voffA[2], voffB[2];
; #pragma unroll
;     for (int i = 0; i < 2; ++i) { int R, C; stage_rc(tid * 16 + i * 8192, R, C); const int Rb = Epi::PERM ? ((R & ~31) + perm32(R & 31)) : R;
;         voffA[i] = (unsigned)(R * K + C) * 2u; voffB[i] = (unsigned)(Rb * K + C) * 2u; }
;     const size_t kstep = (size_t)(BK * 2);
;     const size_t hstep = (size_t)HALF * K * 2;
;     const size_t tstep = 2 * hstep;
;     const unsigned ldsw = (unsigned)wid * 1024u;
;     const int aoff = lds_byte(wr * 64 + fr, fq * 8), boff = lds_byte(wc * 32 + fr, fq * 8);
;     ...
;     Unit cur, nxt; int ui = 0;
;     if (!S.next(0, cur)) return;
;     f32x4 acc[2][2][4][2];
; #pragma unroll
;     for (int a = 0; a < 2; ++a)
; #pragma unroll
;         for (int b = 0; b < 2; ++b)
; #pragma unroll
;             for (int m = 0; m < 4; ++m)
; #pragma unroll
;                 for (int n = 0; n < 2; ++n) acc[a][b][m][n] = (f32x4){0.f, 0.f, 0.f, 0.f};
;     bf16x8 At[4][2], B0[2][2], B1[2][2];
;     const char* cA = (const char*)g.A + (size_t)cur.pm * tstep; const char* cB = (const char*)g.Bt + (size_t)cur.pn * tstep;
;     S.a_ready(cur);
;     if constexpr (SP2) {
;         PG8_STAGE(PG8_SB(0, 0), cB, voffB); PG8_STAGE(PG8_SB(0, 1), cB + hstep, voffB); PG8_STAGE(PG8_SA(0, 0), cA, voffA); PG8_STAGE(PG8_SA(0, 1), cA + hstep, voffA);
;         if (wr == 1) PG8_BAR;
;         PG8_WAIT_V(2); PG8_BAR;
;         PG8_STAGE(PG8_SB(1, 0), cB + kstep, voffB); PG8_STAGE(PG8_SA(1, 0), cA + kstep, voffA); PG8_STAGE(PG8_SB(1, 1), cB + hstep + kstep, voffB);
;         PG8_WAIT_V(6); PG8_BAR;
;     } else {
;         PG8_STAGE(PG8_SB(0, 0), cB, voffB); PG8_STAGE(PG8_SA(0, 0), cA, voffA); PG8_STAGE(PG8_SB(0, 1), cB + hstep, voffB); PG8_STAGE(PG8_SA(0, 1), cA + hstep, voffA);
.LBB0_141:
	s_add_u32 s2, s92, 0x2b00000
	s_addc_u32 s3, s93, 0
	s_add_u32 s96, s92, 0x6b00000
	v_readlane_b32 s4, v244, 2
	s_addc_u32 s97, s93, 0
	s_lshr_b32 s5, s4, 8
	s_lshl_b32 s4, s5, 6
	v_writelane_b32 v244, s4, 17
	v_writelane_b32 v244, s5, 18
	s_lshl_b32 s4, s5, 13
	v_writelane_b32 v244, s4, 19
	s_lshl_b32 s4, s83, 5
	v_writelane_b32 v244, s4, 20
	s_and_b32 s4, s4, 0x60
	s_lshl_b32 s33, s83, 10
	v_writelane_b32 v244, s4, 21
	s_lshr_b32 s4, s4, 3
	s_cmpk_lt_i32 s82, 0xb00
	v_writelane_b32 v244, s4, 22
	s_cselect_b64 s[4:5], -1, 0
	v_writelane_b32 v244, s4, 23
	s_cmpk_gt_i32 s82, 0xaff
	s_waitcnt lgkmcnt(0)
	s_barrier
	s_cselect_b32 s101, 1, 0
	v_mov_b32_e32 v245, 0xc3e80
	global_load_dword v245, v245, s[92:93] sc1
	s_waitcnt vmcnt(0)
	v_readfirstlane_b32 s100, v245
	s_cmp_eq_u32 s100, 0
	s_cselect_b32 s100, 1, 0
	s_cmp_eq_u32 s94, 0x100
	s_cselect_b32 s100, s100, 0
	v_writelane_b32 v244, s100, 61
	s_cmp_lg_u32 s101, 0
	v_writelane_b32 v244, s5, 24
	v_mbcnt_lo_u32_b32 v10, -1, 0
	v_mbcnt_hi_u32_b32 v10, -1, v10
	s_cbranch_scc1 .LBB0_157
	v_lshl_add_u32 v0, v10, 4, s33
	v_add_u32_e32 v1, 0x2000, v0
	v_ashrrev_i32_e32 v2, 31, v1
	v_lshrrev_b32_e32 v2, 22, v2
	v_add_u32_e32 v2, v1, v2
	v_ashrrev_i32_e32 v8, 10, v2
	v_mul_i32_i24_e32 v2, 0x400, v8
	v_sub_u32_e32 v1, v1, v2
	v_lshrrev_b32_e32 v2, 4, v1
	v_bitop3_b32 v1, v2, v1, 32 bitop3:0x6c
	v_ashrrev_i32_e32 v2, 31, v1
	v_lshrrev_b32_e32 v2, 26, v2
	v_add_u32_e32 v2, v1, v2
	v_ashrrev_i32_e32 v9, 6, v2
	v_lshlrev_b32_e32 v3, 3, v8
	v_and_b32_e32 v2, 0xffc0, v2
	v_and_b32_e32 v3, -16, v3
	v_sub_u32_e32 v1, v1, v2
	v_add_u32_e32 v3, v9, v3
	v_lshrrev_b16_e32 v2, 7, v1
	v_and_b32_e32 v4, 3, v9
	s_mov_b32 s4, 0x1fffe0
	v_lshrrev_b32_e32 v5, 2, v3
	v_lshlrev_b32_e32 v6, 1, v3
	v_and_b32_e32 v2, 1, v2
	v_and_or_b32 v4, v3, s4, v4
	v_and_b32_e32 v5, 4, v5
	v_and_b32_e32 v6, 24, v6
	v_add_u16_e32 v1, v1, v2
	v_mov_b32_e32 v2, 1
	v_or3_b32 v4, v4, v5, v6
	v_lshlrev_b32_e32 v5, 5, v8
	v_ashrrev_i16_sdwa v1, v2, sext(v1) dst_sel:DWORD dst_unused:UNUSED_PAD src0_sel:DWORD src1_sel:BYTE_0
	v_and_b32_e32 v5, 32, v5
	v_bfe_i32 v11, v1, 0, 16
	v_add_lshl_u32 v1, v5, v11, 1
	v_lshl_add_u32 v128, v4, 11, v1
	v_lshl_add_u32 v130, v3, 11, v1
	v_ashrrev_i32_e32 v1, 31, v0
	v_lshrrev_b32_e32 v1, 22, v1
	v_add_u32_e32 v1, v0, v1
	v_ashrrev_i32_e32 v12, 10, v1
	v_mul_i32_i24_e32 v1, 0x400, v12
	v_sub_u32_e32 v0, v0, v1
	v_lshrrev_b32_e32 v1, 4, v0
	v_bitop3_b32 v0, v1, v0, 32 bitop3:0x6c
	v_ashrrev_i32_e32 v1, 31, v0
	v_lshrrev_b32_e32 v1, 26, v1
	v_add_u32_e32 v1, v0, v1
	v_lshlrev_b32_e32 v3, 3, v12
	s_add_u32 s40, s92, 0x100000
	v_ashrrev_i32_e32 v13, 6, v1
	v_and_b32_e32 v3, -16, v3
	s_addc_u32 s41, s93, 0
	v_add_u32_e32 v3, v13, v3
	v_and_b32_e32 v4, 3, v13
	s_ashr_i32 s42, s82, 31
	v_and_or_b32 v4, v3, s4, v4
	s_lshr_b32 s4, s42, 29
	s_add_i32 s4, s82, s4
	s_ashr_i32 s5, s4, 3
	s_and_b32 s4, s4, -8
	s_sub_i32 s4, s82, s4
	s_cmp_lt_i32 s4, 0
	s_movk_i32 s43, 0x161
	s_cselect_b32 s6, s43, 0x160
	s_mul_i32 s4, s4, s6
	s_add_i32 s4, s4, s5
	s_mul_hi_i32 s5, s4, 0x2e8ba2e9
	s_lshr_b32 s6, s5, 31
	s_ashr_i32 s5, s5, 4
	s_add_i32 s5, s5, s6
	s_lshl_b32 s6, s5, 2
	s_mulk_i32 s5, 0x58
	s_sub_i32 s5, s4, s5
	s_bfe_i32 s4, s5, 0x80000
	s_bfe_u32 s4, s4, 0x2000d
	s_add_i32 s7, s5, s4
	s_bfe_i32 s4, s7, 0x80000
	s_and_b32 s7, s7, 0xfc
	s_sub_i32 s5, s5, s7
	s_sext_i32_i16 s4, s4
	s_sext_i32_i8 s5, s5
	v_lshrrev_b32_e32 v5, 2, v3
	v_lshlrev_b32_e32 v6, 1, v3
	v_and_b32_e32 v1, 0xc0, v1
	s_lshr_b32 s4, s4, 2
	s_add_i32 s28, s6, s5
	v_and_b32_e32 v5, 4, v5
	v_and_b32_e32 v6, 24, v6
	v_sub_u32_e32 v0, v0, v1
	s_ashr_i32 s29, s28, 31
	s_bfe_i64 s[10:11], s[4:5], 0x100000
	v_or3_b32 v4, v4, v5, v6
	v_lshlrev_b32_e32 v5, 5, v12
	v_ashrrev_i16_sdwa v0, v2, sext(v0) dst_sel:DWORD dst_unused:UNUSED_PAD src0_sel:DWORD src1_sel:BYTE_0
	s_lshl_b64 s[6:7], s[28:29], 19
	s_lshl_b64 s[10:11], s[10:11], 19
	v_and_b32_e32 v5, 32, v5
	v_bfe_i32 v14, v0, 0, 16
	s_add_u32 s34, s40, s10
	v_add_lshl_u32 v0, v5, v14, 1
	s_addc_u32 s35, s41, s11
	s_add_i32 s29, s33, 0
	v_lshl_add_u32 v132, v4, 11, v0
	s_add_i32 m0, s29, 0x10000
	v_lshl_add_u32 v134, v3, 11, v0
	global_load_lds_dwordx4 v132, s[34:35]
	s_add_i32 m0, s29, 0x12000
	s_add_u32 s10, s34, 0x40000
	global_load_lds_dwordx4 v128, s[34:35]
	s_addc_u32 s11, s35, 0
	s_add_i32 m0, s29, 0x14000
	v_mov_b32_e32 v133, 0
	global_load_lds_dwordx4 v132, s[10:11]
	s_add_i32 m0, s29, 0x16000
	s_add_u32 s30, s2, s6
	s_addc_u32 s31, s3, s7
	s_add_i32 s44, s29, 0x2000
	global_load_lds_dwordx4 v128, s[10:11]
	s_mov_b32 m0, s29
	s_add_u32 s6, s30, 0x40000
	global_load_lds_dwordx4 v134, s[30:31]
	s_mov_b32 m0, s44
	s_addc_u32 s7, s31, 0
	s_add_i32 s45, s29, 0x4000
	global_load_lds_dwordx4 v130, s[30:31]
	s_mov_b32 m0, s45
	s_add_i32 s46, s29, 0x6000
	global_load_lds_dwordx4 v134, s[6:7]
	s_mov_b32 m0, s46
	v_readlane_b32 s5, v244, 18
	global_load_lds_dwordx4 v130, s[6:7]
	v_mov_b32_e32 v129, v133
	v_mov_b32_e32 v135, v133
	v_mov_b32_e32 v131, v133
	s_cmp_eq_u32 s5, 1
	s_mov_b32 s47, 0
	v_lshl_add_u64 v[4:5], s[34:35], 0, v[132:133]
	v_lshl_add_u64 v[2:3], s[34:35], 0, v[128:129]
	v_lshl_add_u64 v[0:1], s[30:31], 0, v[134:135]
	s_cselect_b64 s[6:7], -1, 0
	s_cmp_lg_u32 s5, 1
	v_lshl_add_u64 v[6:7], s[30:31], 0, v[130:131]
	s_cbranch_scc1 .LBB0_144
	s_barrier

; __device__ __forceinline__ int lane_now() { int l; asm volatile("v_mbcnt_lo_u32_b32 %0, -1, 0\n\tv_mbcnt_hi_u32_b32 %0, -1, %0" : "=v"(l)); return l; }
; __device__ __forceinline__ unsigned xb_ld(unsigned* p)              { return __hip_atomic_load(p, __ATOMIC_RELAXED, __HIP_MEMORY_SCOPE_AGENT); }
; __device__ __forceinline__ unsigned xb_add(unsigned* p, unsigned v) { return __hip_atomic_fetch_add(p, v, __ATOMIC_RELAXED, __HIP_MEMORY_SCOPE_AGENT); }
; #define XB_SPIN(cond, bar) do { unsigned _sp = 0; while (cond) { __builtin_amdgcn_s_sleep(1); \
;     if ((++_sp & 255u) == 0u) { if (xb_ld(&(bar)[XB_TMO])) break; if (_sp > XB_SPIN_CAP) { atomicAdd(&(bar)[XB_TMO], 1u); break; } } } } while (0)
; __device__ __forceinline__ void xcd_barrier(const XcdBarrier& b) {
;     asm volatile("s_waitcnt vmcnt(0)" ::: "memory");
;     __syncthreads();
;     if (b.w0 && lane_now() == 0) {
;         unsigned* bar = b.bar;
;         __builtin_amdgcn_s_waitcnt(0);
;         unsigned nloc = b.st[0], nx = b.st[1];
;         if (nloc == 0u) { xcd_barrier_complete(bar, b.x, nloc, nx); b.st[0] = nloc; b.st[1] = nx; }
;         const unsigned old = xb_add(&bar[XB_XSUB(b.x)], 1u);
;         const unsigned gen = old / nloc;
;         if (old + 1u == (gen + 1u) * nloc) {
;             __builtin_amdgcn_fence(__ATOMIC_RELEASE, "agent");
;             asm volatile("s_waitcnt vmcnt(0)" ::: "memory");
;             const unsigned og = xb_add(&bar[XB_TOP], 1u);
;             const unsigned tg = og / nx;
;             if (og + 1u == (tg + 1u) * nx) xb_add(&bar[XB_TOPGEN], 1u);
;             else XB_SPIN(xb_ld(&bar[XB_TOPGEN]) == tg, bar);
;             __builtin_amdgcn_fence(__ATOMIC_ACQUIRE, "agent");
;             xb_add(&bar[XB_XGEN(b.x)], 1u);
;             asm volatile("s_waitcnt vmcnt(0)" ::: "memory");
;         } else {
;             XB_SPIN(xb_ld(&bar[XB_XGEN(b.x)]) == gen, bar);
;             __builtin_amdgcn_fence(__ATOMIC_ACQUIRE, "agent");
;             asm volatile("s_waitcnt vmcnt(0)" ::: "memory");
;         }
.LBB0_272:
	s_andn2_saveexec_b64 s[10:11], s[10:11]
	s_cbranch_execz .LBB0_292
	s_mov_b64 s[10:11], exec
	v_readlane_b32 s100, v244, 61
	s_cmp_lg_u32 s100, 0
	s_cbranch_scc1 .LBB0_289
	buffer_wbl2 sc1
	s_waitcnt lgkmcnt(0)
	s_waitcnt vmcnt(0)
	v_mbcnt_lo_u32_b32 v1, s10, 0
	v_mbcnt_hi_u32_b32 v1, s11, v1
	v_cmp_eq_u32_e32 vcc, 0, v1
	s_and_saveexec_b64 s[16:17], vcc
	s_cbranch_execz .LBB0_275
	s_bcnt1_i32_b64 s10, s[10:11]
	v_mov_b32_e32 v2, 0xc3000
	v_mov_b32_e32 v3, s10
	global_atomic_add v2, v2, v3, s[92:93] offset:1024 sc0
.LBB0_275:
	s_or_b64 exec, exec, s[16:17]
	v_cvt_f32_u32_e32 v3, v0
	s_waitcnt vmcnt(0)
	v_readfirstlane_b32 s10, v2
	s_add_u32 s16, s92, 0xc3500
	s_addc_u32 s17, s93, 0
	v_rcp_iflag_f32_e32 v3, v3
	v_add_u32_e32 v1, s10, v1
	v_add_u32_e32 v4, 1, v1
	s_mov_b64 s[20:21], -1
	v_mul_f32_e32 v2, 0x4f7ffffe, v3
	v_cvt_u32_f32_e32 v2, v2
	v_sub_u32_e32 v3, 0, v0
	v_mul_lo_u32 v3, v3, v2
	v_mul_hi_u32 v3, v2, v3
	v_add_u32_e32 v2, v2, v3
	v_mul_hi_u32 v2, v1, v2
	v_mul_lo_u32 v3, v2, v0
	v_sub_u32_e32 v1, v1, v3
	v_add_u32_e32 v5, 1, v2
	v_cmp_ge_u32_e32 vcc, v1, v0
	v_sub_u32_e32 v3, v1, v0
	s_nop 0
	v_cndmask_b32_e32 v2, v2, v5, vcc
	v_cndmask_b32_e32 v1, v1, v3, vcc
	v_add_u32_e32 v3, 1, v2
	v_cmp_ge_u32_e32 vcc, v1, v0
	s_nop 1
	v_cndmask_b32_e32 v2, v2, v3, vcc
	v_mul_lo_u32 v1, v0, v2
	v_add_u32_e32 v0, v1, v0
	v_cmp_ne_u32_e32 vcc, v4, v0
	v_mov_b64_e32 v[0:1], s[16:17]
	s_and_saveexec_b64 s[10:11], vcc
	s_cbranch_execz .LBB0_287
	v_mov_b32_e32 v0, 0
	global_load_dword v1, v0, s[16:17] sc1
	s_mov_b64 s[24:25], 0
	s_waitcnt vmcnt(0)
	v_cmp_eq_u32_e32 vcc, v1, v2
	s_and_saveexec_b64 s[22:23], vcc
	s_cbranch_execz .LBB0_286
	s_add_u32 s20, s92, 0xc0200
	s_addc_u32 s21, s93, 0
	s_mov_b32 s36, 1
	s_branch .LBB0_279

; #define LAS __attribute__((address_space(3)))
; __device__ __forceinline__ unsigned pk2(float lo, float hi) { const f32x2c v = {lo, hi}; const bf16x2c b = __builtin_convertvector(v, bf16x2c); return __builtin_bit_cast(unsigned, b); }
; #define lane (lane_now())
; __device__ __forceinline__ void norm_phase(const float* src, const float* g, const float* mod, int ish, int isc, bf16_t* dst, LAS unsigned char* lds, int gw, int ngw, int wave, int lane) {
;     ...
;     for (int m = gw; m < MTOK; m += ngw) {
;         const f32x4* xr = (const f32x4*)(src + (size_t)m * DM) + lane;
;         f32x4 v[4]; float s = 0.f;
; #pragma unroll
;         for (int j = 0; j < 4; ++j) { v[j] = xr[64 * j]; s += (v[j].x * v[j].x + v[j].y * v[j].y) + (v[j].z * v[j].z + v[j].w * v[j].w); }
;         s = wave_sum(s);
;         const float rstd = rsqrtf(s * (1.f / DM) + 1e-6f);
;         const int bo = (m >> 13) * 1024;
;         u32x2* o8 = (u32x2*)(dst + (size_t)m * DM) + lane;
; #pragma unroll
;         for (int j = 0; j < 4; ++j) { const int c = bo + 4 * lane + 256 * j;
;             const f32x4 gg = *(const LAS f32x4*)(GSl + c), h4 = *(const LAS f32x4*)(SHl + c);
;             const f32x4 o = v[j] * rstd * gg + h4;
;             u32x2 w; w.x = pk2(o.x, o.y); w.y = pk2(o.z, o.w); o8[64 * j] = w; }
;     }
.LBB0_307:
	s_or_b64 exec, exec, s[10:11]
	s_waitcnt lgkmcnt(0)
	s_barrier
	v_cndmask_b32_e64 v1, 0, 1, s[0:1]
	v_cmp_ne_u32_e64 s[4:5], 1, v1
	s_andn2_b64 vcc, exec, s[0:1]
	s_nop 0
	v_writelane_b32 v244, s4, 27
	s_nop 1
	v_writelane_b32 v244, s5, 28
	s_cbranch_vccnz .LBB0_310
	s_mov_b32 s100, s78
	s_mov_b32 s101, s84
	s_mov_b32 s98, 0x8000
	v_readlane_b32 s99, v244, 61
	s_cmp_eq_u32 s99, 0
	s_cbranch_scc1 .Lxn_keep309
	s_lshr_b32 s99, s100, 3
	s_and_b32 s98, s99, 7
	s_lshl_b32 s98, s98, 12
	s_and_b32 s99, s99, 0xfffffff8
	s_and_b32 s78, s100, 7
	s_add_i32 s78, s78, s99
	s_add_i32 s78, s78, s98
	s_add_i32 s98, s98, 0x1000
	s_movk_i32 s84, 0x100
.Lxn_keep309:
	v_mbcnt_hi_u32_b32 v2, -1, v204
	v_and_b32_e32 v3, 64, v2
	v_add_u32_e32 v3, 64, v3
	v_xor_b32_e32 v4, 1, v2
	v_cmp_lt_i32_e32 vcc, v4, v3
	v_xor_b32_e32 v5, 2, v2
	v_xor_b32_e32 v6, 4, v2
	v_cndmask_b32_e32 v4, v2, v4, vcc
	v_cmp_lt_i32_e32 vcc, v5, v3
	v_xor_b32_e32 v7, 8, v2
	v_xor_b32_e32 v8, 16, v2
	v_cndmask_b32_e32 v5, v2, v5, vcc
	v_cmp_lt_i32_e32 vcc, v6, v3
	s_ashr_i32 s79, s78, 31
	v_xor_b32_e32 v9, 32, v2
	v_cndmask_b32_e32 v6, v2, v6, vcc
	v_cmp_lt_i32_e32 vcc, v7, v3
	s_lshl_b64 s[0:1], s[78:79], 11
	s_add_u32 s0, s92, s0
	v_cndmask_b32_e32 v7, v2, v7, vcc
	v_cmp_lt_i32_e32 vcc, v8, v3
	v_ashrrev_i32_e32 v1, 31, v0
	s_addc_u32 s1, s93, s1
	v_cndmask_b32_e32 v8, v2, v8, vcc
	v_cmp_lt_i32_e32 vcc, v9, v3
	s_ashr_i32 s85, s84, 31
	s_lshl_b64 s[4:5], s[78:79], 12
	v_cndmask_b32_e32 v2, v2, v9, vcc
	v_lshlrev_b32_e32 v9, 2, v2
	v_lshl_add_u64 v[2:3], v[0:1], 3, s[0:1]
	s_mov_b64 s[0:1], 0x2b00000
	v_lshl_add_u64 v[2:3], v[2:3], 0, s[0:1]
	s_lshl_b64 s[0:1], s[84:85], 11
	s_add_u32 s4, s90, s4
	s_addc_u32 s5, s91, s5
	v_lshlrev_b32_e32 v10, 2, v0
	v_lshl_add_u64 v[0:1], v[0:1], 4, s[4:5]
	s_mov_b64 s[4:5], 0xc00
	v_lshlrev_b32_e32 v4, 2, v4
	v_lshlrev_b32_e32 v5, 2, v5
	v_lshlrev_b32_e32 v6, 2, v6
	v_lshlrev_b32_e32 v7, 2, v7
	v_lshlrev_b32_e32 v8, 2, v8
	v_lshl_add_u64 v[0:1], v[0:1], 0, s[4:5]
	s_lshl_b64 s[4:5], s[84:85], 12
	v_mov_b32_e32 v11, 0x358637bd
	s_mov_b32 s6, 0x800000
	s_mov_b32 s7, s78
.LBB0_309:
	global_load_dwordx4 v[12:15], v[0:1], off offset:-3072
	global_load_dwordx4 v[16:19], v[0:1], off offset:-2048
	global_load_dwordx4 v[20:23], v[0:1], off offset:-1024
	global_load_dwordx4 v[24:27], v[0:1], off
	s_ashr_i32 s8, s7, 3
	s_and_b32 s8, s8, 0x3ffffc00
	v_add_u32_e32 v28, s8, v10
	v_lshl_add_u32 v56, v28, 2, 0
	ds_read_b128 v[28:31], v56
	ds_read_b128 v[32:35], v56 offset:1024
	ds_read_b128 v[36:39], v56 offset:16384
	ds_read_b128 v[40:43], v56 offset:17408
	ds_read_b128 v[44:47], v56 offset:2048
	ds_read_b128 v[48:51], v56 offset:3072
	ds_read_b128 v[52:55], v56 offset:18432
	ds_read_b128 v[56:59], v56 offset:19456
	s_add_i32 s7, s7, s84
	v_lshl_add_u64 v[0:1], v[0:1], 0, s[4:5]
	s_cmp_lt_i32 s7, s98
	s_waitcnt vmcnt(3)
	v_pk_mul_f32 v[60:61], v[14:15], v[14:15]
	v_pk_mul_f32 v[62:63], v[12:13], v[12:13]
	s_waitcnt vmcnt(2)
	v_pk_mul_f32 v[64:65], v[18:19], v[18:19]
	v_pk_mul_f32 v[66:67], v[16:17], v[16:17]
	v_pk_mov_b32 v[72:73], v[62:63], v[60:61] op_sel:[1,0]
	v_mov_b32_e32 v63, v61
	v_pk_mov_b32 v[60:61], v[66:67], v[64:65] op_sel:[1,0]
	v_mov_b32_e32 v67, v65
	s_waitcnt vmcnt(0)
	v_mul_f32_e32 v71, v24, v24
	v_mul_f32_e32 v68, v21, v21
	v_mul_f32_e32 v70, v23, v23
	v_pk_add_f32 v[62:63], v[72:73], v[62:63]
	v_pk_add_f32 v[60:61], v[60:61], v[66:67]
	v_mul_f32_e32 v74, v25, v25
	v_mul_f32_e32 v75, v26, v26
	v_mul_f32_e32 v76, v27, v27
	v_pk_fma_f32 v[64:65], v[20:21], v[20:21], v[68:69] op_sel_hi:[1,1,0]
	v_pk_fma_f32 v[68:69], v[22:23], v[22:23], v[70:71] op_sel_hi:[1,1,0]
	v_pk_add_f32 v[62:63], v[62:63], v[62:63] op_sel:[0,1] op_sel_hi:[1,0]
	v_pk_add_f32 v[60:61], v[60:61], v[60:61] op_sel:[0,1] op_sel_hi:[1,0]
	v_mov_b32_e32 v65, v75
	v_mov_b32_e32 v69, v76
	v_mov_b32_e32 v63, v71
	v_mov_b32_e32 v61, v74
	v_pk_add_f32 v[64:65], v[64:65], v[68:69]
	v_pk_add_f32 v[60:61], v[62:63], v[60:61]
	s_nop 0
	v_pk_add_f32 v[60:61], v[60:61], v[64:65]
	s_nop 0
	v_add_f32_e32 v60, v60, v61
	ds_bpermute_b32 v61, v4, v60
	s_waitcnt lgkmcnt(0)
	v_add_f32_e32 v60, v60, v61
	ds_bpermute_b32 v61, v5, v60
	s_waitcnt lgkmcnt(0)
	v_add_f32_e32 v60, v60, v61
	ds_bpermute_b32 v61, v6, v60
	s_waitcnt lgkmcnt(0)
	v_add_f32_e32 v60, v60, v61
	ds_bpermute_b32 v61, v7, v60
	s_waitcnt lgkmcnt(0)
	v_add_f32_e32 v60, v60, v61
	ds_bpermute_b32 v61, v8, v60
	s_waitcnt lgkmcnt(0)
	v_add_f32_e32 v60, v60, v61
	ds_bpermute_b32 v61, v9, v60
	s_waitcnt lgkmcnt(0)
	v_add_f32_e32 v60, v60, v61
	v_fmamk_f32 v60, v60, 0x3a800000, v11
	v_mul_f32_e32 v61, 0x4b800000, v60
	v_cmp_gt_f32_e32 vcc, s6, v60
	s_nop 1
	v_cndmask_b32_e32 v60, v60, v61, vcc
	v_rsq_f32_e32 v60, v60
	s_nop 0
	v_mul_f32_e32 v61, 0x45800000, v60
	v_cndmask_b32_e32 v60, v60, v61, vcc
	v_pk_mul_f32 v[12:13], v[12:13], v[60:61] op_sel_hi:[1,0]
	v_pk_mul_f32 v[14:15], v[14:15], v[60:61] op_sel_hi:[1,0]
	v_pk_mul_f32 v[16:17], v[16:17], v[60:61] op_sel_hi:[1,0]
	v_pk_mul_f32 v[18:19], v[18:19], v[60:61] op_sel_hi:[1,0]
	v_pk_mul_f32 v[20:21], v[20:21], v[60:61] op_sel_hi:[1,0]
	v_pk_mul_f32 v[22:23], v[22:23], v[60:61] op_sel_hi:[1,0]
	v_pk_mul_f32 v[24:25], v[24:25], v[60:61] op_sel_hi:[1,0]
	v_pk_mul_f32 v[26:27], v[26:27], v[60:61] op_sel_hi:[1,0]
	v_pk_fma_f32 v[14:15], v[30:31], v[14:15], v[38:39]
	v_pk_fma_f32 v[12:13], v[28:29], v[12:13], v[36:37]
	v_pk_fma_f32 v[18:19], v[34:35], v[18:19], v[42:43]
	v_pk_fma_f32 v[16:17], v[32:33], v[16:17], v[40:41]
	v_pk_fma_f32 v[22:23], v[46:47], v[22:23], v[54:55]
	v_pk_fma_f32 v[20:21], v[44:45], v[20:21], v[52:53]
	v_pk_fma_f32 v[26:27], v[50:51], v[26:27], v[58:59]
	v_pk_fma_f32 v[24:25], v[48:49], v[24:25], v[56:57]
	v_cvt_pk_bf16_f32 v12, v12, v13
	v_cvt_pk_bf16_f32 v13, v14, v15
	v_cvt_pk_bf16_f32 v14, v16, v17
	v_cvt_pk_bf16_f32 v15, v18, v19
	v_cvt_pk_bf16_f32 v16, v20, v21
	v_cvt_pk_bf16_f32 v17, v22, v23
	v_cvt_pk_bf16_f32 v18, v24, v25
	v_cvt_pk_bf16_f32 v19, v26, v27
	global_store_dwordx2 v[2:3], v[12:13], off
	global_store_dwordx2 v[2:3], v[14:15], off offset:512
	global_store_dwordx2 v[2:3], v[16:17], off offset:1024
	global_store_dwordx2 v[2:3], v[18:19], off offset:1536
	v_lshl_add_u64 v[2:3], v[2:3], 0, s[0:1]
	s_cbranch_scc1 .LBB0_309
	s_mov_b32 s78, s100
	s_mov_b32 s84, s101

; __device__ __forceinline__ int lane_now() { int l; asm volatile("v_mbcnt_lo_u32_b32 %0, -1, 0\n\tv_mbcnt_hi_u32_b32 %0, -1, %0" : "=v"(l)); return l; }
; __device__ __forceinline__ unsigned xb_ld(unsigned* p)              { return __hip_atomic_load(p, __ATOMIC_RELAXED, __HIP_MEMORY_SCOPE_AGENT); }
; __device__ __forceinline__ unsigned xb_add(unsigned* p, unsigned v) { return __hip_atomic_fetch_add(p, v, __ATOMIC_RELAXED, __HIP_MEMORY_SCOPE_AGENT); }
; #define XB_SPIN(cond, bar) do { unsigned _sp = 0; while (cond) { __builtin_amdgcn_s_sleep(1); \
;     if ((++_sp & 255u) == 0u) { if (xb_ld(&(bar)[XB_TMO])) break; if (_sp > XB_SPIN_CAP) { atomicAdd(&(bar)[XB_TMO], 1u); break; } } } } while (0)
; __device__ __forceinline__ void xcd_barrier(const XcdBarrier& b) {
;     asm volatile("s_waitcnt vmcnt(0)" ::: "memory");
;     __syncthreads();
;     if (b.w0 && lane_now() == 0) {
;         unsigned* bar = b.bar;
;         __builtin_amdgcn_s_waitcnt(0);
;         unsigned nloc = b.st[0], nx = b.st[1];
;         if (nloc == 0u) { xcd_barrier_complete(bar, b.x, nloc, nx); b.st[0] = nloc; b.st[1] = nx; }
;         const unsigned old = xb_add(&bar[XB_XSUB(b.x)], 1u);
;         const unsigned gen = old / nloc;
;         if (old + 1u == (gen + 1u) * nloc) {
;             __builtin_amdgcn_fence(__ATOMIC_RELEASE, "agent");
;             asm volatile("s_waitcnt vmcnt(0)" ::: "memory");
;             const unsigned og = xb_add(&bar[XB_TOP], 1u);
;             const unsigned tg = og / nx;
;             if (og + 1u == (tg + 1u) * nx) xb_add(&bar[XB_TOPGEN], 1u);
;             else XB_SPIN(xb_ld(&bar[XB_TOPGEN]) == tg, bar);
;             __builtin_amdgcn_fence(__ATOMIC_ACQUIRE, "agent");
;             xb_add(&bar[XB_XGEN(b.x)], 1u);
.LBB0_1210:
	s_andn2_saveexec_b64 s[8:9], s[8:9]
	s_cbranch_execz .LBB0_1230
	s_mov_b64 s[8:9], exec
	v_readlane_b32 s100, v244, 61
	s_cmp_lg_u32 s100, 0
	s_cbranch_scc1 .LBB0_1227
	buffer_wbl2 sc1
	s_waitcnt lgkmcnt(0)
	s_waitcnt vmcnt(0)
	v_mbcnt_lo_u32_b32 v1, s8, 0
	v_mbcnt_hi_u32_b32 v1, s9, v1
	v_cmp_eq_u32_e32 vcc, 0, v1
	s_and_saveexec_b64 s[10:11], vcc
	s_cbranch_execz .LBB0_1213
	s_bcnt1_i32_b64 s8, s[8:9]
	v_mov_b32_e32 v2, 0xc3000
	v_mov_b32_e32 v3, s8
	global_atomic_add v2, v2, v3, s[92:93] offset:1024 sc0

; #define LAS __attribute__((address_space(3)))
; __device__ __forceinline__ unsigned pk2(float lo, float hi) { const f32x2c v = {lo, hi}; const bf16x2c b = __builtin_convertvector(v, bf16x2c); return __builtin_bit_cast(unsigned, b); }
; #define lane (lane_now())
; __device__ __forceinline__ void norm_phase(const float* src, const float* g, const float* mod, int ish, int isc, bf16_t* dst, LAS unsigned char* lds, int gw, int ngw, int wave, int lane) {
;     ...
;     for (int m = gw; m < MTOK; m += ngw) {
;         const f32x4* xr = (const f32x4*)(src + (size_t)m * DM) + lane;
;         f32x4 v[4]; float s = 0.f;
; #pragma unroll
;         for (int j = 0; j < 4; ++j) { v[j] = xr[64 * j]; s += (v[j].x * v[j].x + v[j].y * v[j].y) + (v[j].z * v[j].z + v[j].w * v[j].w); }
;         s = wave_sum(s);
;         const float rstd = rsqrtf(s * (1.f / DM) + 1e-6f);
;         const int bo = (m >> 13) * 1024;
;         u32x2* o8 = (u32x2*)(dst + (size_t)m * DM) + lane;
; #pragma unroll
;         for (int j = 0; j < 4; ++j) { const int c = bo + 4 * lane + 256 * j;
;             const f32x4 gg = *(const LAS f32x4*)(GSl + c), h4 = *(const LAS f32x4*)(SHl + c);
;             const f32x4 o = v[j] * rstd * gg + h4;
;             u32x2 w; w.x = pk2(o.x, o.y); w.y = pk2(o.z, o.w); o8[64 * j] = w; }
;     }
.LBB0_1245:
	s_or_b64 exec, exec, s[0:1]
	s_waitcnt lgkmcnt(0)
	s_barrier
	v_readlane_b32 s0, v244, 27
	v_readlane_b32 s1, v244, 28
	s_and_b64 vcc, exec, s[0:1]
	s_cbranch_vccnz .LBB0_1248
	s_mov_b32 s100, s78
	s_mov_b32 s101, s84
	s_mov_b32 s98, 0x8000
	v_readlane_b32 s99, v244, 61
	s_cmp_eq_u32 s99, 0
	s_cbranch_scc1 .Lxn_keep1247
	s_lshr_b32 s99, s100, 3
	s_and_b32 s98, s99, 7
	s_lshl_b32 s98, s98, 12
	s_and_b32 s99, s99, 0xfffffff8
	s_and_b32 s78, s100, 7
	s_add_i32 s78, s78, s99
	s_add_i32 s78, s78, s98
	s_add_i32 s98, s98, 0x1000
	s_movk_i32 s84, 0x100
.Lxn_keep1247:
	v_and_b32_e32 v2, 64, v166
	v_add_u32_e32 v2, 64, v2
	v_xor_b32_e32 v3, 1, v166
	v_cmp_lt_i32_e32 vcc, v3, v2
	s_ashr_i32 s79, s78, 31
	s_lshl_b64 s[0:1], s[78:79], 11
	v_cndmask_b32_e32 v3, v166, v3, vcc
	v_lshlrev_b32_e32 v4, 2, v3
	v_xor_b32_e32 v3, 2, v166
	v_cmp_lt_i32_e32 vcc, v3, v2
	s_add_u32 s0, s92, s0
	v_ashrrev_i32_e32 v1, 31, v0
	v_cndmask_b32_e32 v3, v166, v3, vcc
	v_lshlrev_b32_e32 v5, 2, v3
	v_xor_b32_e32 v3, 4, v166
	v_cmp_lt_i32_e32 vcc, v3, v2
	s_addc_u32 s1, s93, s1
	s_ashr_i32 s85, s84, 31
	v_cndmask_b32_e32 v3, v166, v3, vcc
	v_lshlrev_b32_e32 v6, 2, v3
	v_xor_b32_e32 v3, 8, v166
	v_cmp_lt_i32_e32 vcc, v3, v2
	s_lshl_b64 s[6:7], s[78:79], 12
	v_lshlrev_b32_e32 v10, 2, v0
	v_cndmask_b32_e32 v3, v166, v3, vcc
	v_lshlrev_b32_e32 v7, 2, v3
	v_xor_b32_e32 v3, 16, v166
	v_cmp_lt_i32_e32 vcc, v3, v2
	v_mov_b32_e32 v11, 0x358637bd
	s_mov_b32 s8, 0x800000
	v_cndmask_b32_e32 v3, v166, v3, vcc
	v_lshlrev_b32_e32 v8, 2, v3
	v_xor_b32_e32 v3, 32, v166
	v_cmp_lt_i32_e32 vcc, v3, v2
	s_nop 1
	v_cndmask_b32_e32 v2, v166, v3, vcc
	v_lshlrev_b32_e32 v9, 2, v2
	v_lshl_add_u64 v[2:3], v[0:1], 3, s[0:1]
	s_mov_b64 s[0:1], 0x2b00000
	v_lshl_add_u64 v[2:3], v[2:3], 0, s[0:1]
	s_lshl_b64 s[0:1], s[84:85], 11
	s_add_u32 s6, s90, s6
	s_addc_u32 s7, s91, s7
	v_lshl_add_u64 v[0:1], v[0:1], 4, s[6:7]
	s_mov_b64 s[6:7], 0xc00
	v_lshl_add_u64 v[0:1], v[0:1], 0, s[6:7]
	s_lshl_b64 s[6:7], s[84:85], 12
.LBB0_1247:
	global_load_dwordx4 v[12:15], v[0:1], off offset:-3072
	global_load_dwordx4 v[16:19], v[0:1], off offset:-2048
	global_load_dwordx4 v[20:23], v[0:1], off offset:-1024
	global_load_dwordx4 v[24:27], v[0:1], off
	s_ashr_i32 s9, s78, 3
	s_and_b32 s9, s9, 0x3ffffc00
	v_add_u32_e32 v28, s9, v10
	v_lshl_add_u32 v56, v28, 2, 0
	ds_read_b128 v[28:31], v56
	ds_read_b128 v[32:35], v56 offset:1024
	ds_read_b128 v[36:39], v56 offset:16384
	ds_read_b128 v[40:43], v56 offset:17408
	ds_read_b128 v[44:47], v56 offset:2048
	ds_read_b128 v[48:51], v56 offset:3072
	ds_read_b128 v[52:55], v56 offset:18432
	ds_read_b128 v[56:59], v56 offset:19456
	s_add_i32 s78, s78, s84
	v_lshl_add_u64 v[0:1], v[0:1], 0, s[6:7]
	s_cmp_lt_i32 s78, s98
	s_waitcnt vmcnt(3)
	v_pk_mul_f32 v[60:61], v[14:15], v[14:15]
	v_pk_mul_f32 v[62:63], v[12:13], v[12:13]
	s_waitcnt vmcnt(2)
	v_pk_mul_f32 v[64:65], v[18:19], v[18:19]
	v_pk_mul_f32 v[66:67], v[16:17], v[16:17]
	v_pk_mov_b32 v[72:73], v[62:63], v[60:61] op_sel:[1,0]
	v_mov_b32_e32 v63, v61
	v_pk_mov_b32 v[60:61], v[66:67], v[64:65] op_sel:[1,0]
	v_mov_b32_e32 v67, v65
	s_waitcnt vmcnt(0)
	v_mul_f32_e32 v71, v24, v24
	v_mul_f32_e32 v68, v21, v21
	v_mul_f32_e32 v70, v23, v23
	v_pk_add_f32 v[62:63], v[72:73], v[62:63]
	v_pk_add_f32 v[60:61], v[60:61], v[66:67]
	v_mul_f32_e32 v74, v25, v25
	v_mul_f32_e32 v75, v26, v26
	v_mul_f32_e32 v76, v27, v27
	v_pk_fma_f32 v[64:65], v[20:21], v[20:21], v[68:69] op_sel_hi:[1,1,0]
	v_pk_fma_f32 v[68:69], v[22:23], v[22:23], v[70:71] op_sel_hi:[1,1,0]
	v_pk_add_f32 v[62:63], v[62:63], v[62:63] op_sel:[0,1] op_sel_hi:[1,0]
	v_pk_add_f32 v[60:61], v[60:61], v[60:61] op_sel:[0,1] op_sel_hi:[1,0]
	v_mov_b32_e32 v65, v75
	v_mov_b32_e32 v69, v76
	v_mov_b32_e32 v63, v71
	v_mov_b32_e32 v61, v74
	v_pk_add_f32 v[64:65], v[64:65], v[68:69]
	v_pk_add_f32 v[60:61], v[62:63], v[60:61]
	s_nop 0
	v_pk_add_f32 v[60:61], v[60:61], v[64:65]
	s_nop 0
	v_add_f32_e32 v60, v60, v61
	ds_bpermute_b32 v61, v4, v60
	s_waitcnt lgkmcnt(0)
	v_add_f32_e32 v60, v60, v61
	ds_bpermute_b32 v61, v5, v60
	s_waitcnt lgkmcnt(0)
	v_add_f32_e32 v60, v60, v61
	ds_bpermute_b32 v61, v6, v60
	s_waitcnt lgkmcnt(0)
	v_add_f32_e32 v60, v60, v61
	ds_bpermute_b32 v61, v7, v60
	s_waitcnt lgkmcnt(0)
	v_add_f32_e32 v60, v60, v61
	ds_bpermute_b32 v61, v8, v60
	s_waitcnt lgkmcnt(0)
	v_add_f32_e32 v60, v60, v61
	ds_bpermute_b32 v61, v9, v60
	s_waitcnt lgkmcnt(0)
	v_add_f32_e32 v60, v60, v61
	v_fmamk_f32 v60, v60, 0x3a800000, v11
	v_mul_f32_e32 v61, 0x4b800000, v60
	v_cmp_gt_f32_e32 vcc, s8, v60
	s_nop 1
	v_cndmask_b32_e32 v60, v60, v61, vcc
	v_rsq_f32_e32 v60, v60
	s_nop 0
	v_mul_f32_e32 v61, 0x45800000, v60
	v_cndmask_b32_e32 v60, v60, v61, vcc
	v_pk_mul_f32 v[12:13], v[12:13], v[60:61] op_sel_hi:[1,0]
	v_pk_mul_f32 v[14:15], v[14:15], v[60:61] op_sel_hi:[1,0]
	v_pk_mul_f32 v[16:17], v[16:17], v[60:61] op_sel_hi:[1,0]
	v_pk_mul_f32 v[18:19], v[18:19], v[60:61] op_sel_hi:[1,0]
	v_pk_mul_f32 v[20:21], v[20:21], v[60:61] op_sel_hi:[1,0]
	v_pk_mul_f32 v[22:23], v[22:23], v[60:61] op_sel_hi:[1,0]
	v_pk_mul_f32 v[24:25], v[24:25], v[60:61] op_sel_hi:[1,0]
	v_pk_mul_f32 v[26:27], v[26:27], v[60:61] op_sel_hi:[1,0]
	v_pk_fma_f32 v[14:15], v[30:31], v[14:15], v[38:39]
	v_pk_fma_f32 v[12:13], v[28:29], v[12:13], v[36:37]
	v_pk_fma_f32 v[18:19], v[34:35], v[18:19], v[42:43]
	v_pk_fma_f32 v[16:17], v[32:33], v[16:17], v[40:41]
	v_pk_fma_f32 v[22:23], v[46:47], v[22:23], v[54:55]
	v_pk_fma_f32 v[20:21], v[44:45], v[20:21], v[52:53]
	v_pk_fma_f32 v[26:27], v[50:51], v[26:27], v[58:59]
	v_pk_fma_f32 v[24:25], v[48:49], v[24:25], v[56:57]
	v_cvt_pk_bf16_f32 v12, v12, v13
	v_cvt_pk_bf16_f32 v13, v14, v15
	v_cvt_pk_bf16_f32 v14, v16, v17
	v_cvt_pk_bf16_f32 v15, v18, v19
	v_cvt_pk_bf16_f32 v16, v20, v21
	v_cvt_pk_bf16_f32 v17, v22, v23
	v_cvt_pk_bf16_f32 v18, v24, v25
	v_cvt_pk_bf16_f32 v19, v26, v27
	global_store_dwordx2 v[2:3], v[12:13], off
	global_store_dwordx2 v[2:3], v[14:15], off offset:512
	global_store_dwordx2 v[2:3], v[16:17], off offset:1024
	global_store_dwordx2 v[2:3], v[18:19], off offset:1536
	v_lshl_add_u64 v[2:3], v[2:3], 0, s[0:1]
	s_cbranch_scc1 .LBB0_1247
	s_add_i32 s78, s100, 0x8000
	s_mov_b32 s84, s101
